# one static s_setprio 1 at kernel entry for waves 4-7 (trailing half), all 120 per-block priority flips deleted
# speedup vs baseline: 1.0002x; 1.0002x over previous
_Z14fwd_megakernel6Params:
	s_mov_b64 s[92:93], s[0:1]
	v_readfirstlane_b32 s3, v0
	s_nop 3
	s_bfe_u32 s3, s3, 0x40006
	s_cmp_ge_u32 s3, 4
	s_cbranch_scc0 .Lprio_done
	s_setprio 1
.Lprio_done:
	s_load_dwordx4 s[60:63], s[0:1], 0xa8
	s_load_dwordx2 s[96:97], s[0:1], 0xb8
	s_add_u32 s0, s92, 0xb8
	s_addc_u32 s1, s93, 0
	v_and_b32_e32 v2, 63, v0
	v_writelane_b32 v253, s0, 0
	s_mov_b32 s90, s2
	v_and_b32_e32 v1, 0x3ff, v0
	v_writelane_b32 v253, s1, 1
	v_cmp_eq_u32_e32 vcc, 0, v2
	s_and_saveexec_b64 s[0:1], vcc
	s_cbranch_execz .LBB0_2
	s_getreg_b32 s3, hwreg(HW_REG_HW_ID, 0, 6)
	s_and_b32 s3, s3, 63
	s_lshl_b32 s3, s3, 2
	s_add_i32 s3, s3, 0
	s_add_i32 s3, s3, 0x20200
	v_lshrrev_b32_e32 v2, 6, v1
	v_mov_b32_e32 v3, s3
	ds_write_b32 v3, v2

.LBB0_333:
	s_add_i32 s56, s8, 2
	s_add_u32 s9, s6, 0x8000
	s_addc_u32 s10, s7, 0
	s_cmp_eq_u32 s94, s8
	s_cselect_b32 s11, s43, s10
	s_cselect_b32 s10, s42, s9
	s_cselect_b32 s60, s54, s24
	s_cselect_b32 s61, s55, s38
	s_add_u32 s8, s10, 0x8000
	s_addc_u32 s9, s11, 0
	s_add_i32 s35, 0, 0x10000
	s_add_i32 s57, 0, 0x14000
	v_add_u32_e32 v142, s35, v178
	v_add_u32_e32 v168, s57, v178
	ds_read_b128 v[128:131], v142
	ds_read_b128 v[132:135], v142 offset:1024
	ds_read_b128 v[136:139], v142 offset:2048
	ds_read_b128 v[142:145], v142 offset:3072
	ds_read_b128 v[146:149], v168
	ds_read_b128 v[150:153], v168 offset:1024
	ds_read_b128 v[154:157], v168 offset:2048
	ds_read_b128 v[168:171], v168 offset:3072
	v_lshl_add_u64 v[176:177], s[6:7], 0, v[164:165]
	s_add_i32 m0, s75, 0xc000
	ds_read_b128 v[172:175], v179
	ds_read_b128 v[180:183], v179 offset:1024
	ds_read_b128 v[184:187], v179 offset:2048
	ds_read_b128 v[188:191], v179 offset:3072
	ds_read_b128 v[192:195], v179 offset:4096
	ds_read_b128 v[200:203], v179 offset:5120
	ds_read_b128 v[206:209], v179 offset:6144
	ds_read_b128 v[210:213], v179 offset:7168
	global_load_lds_dwordx4 v[176:177], off
	v_lshl_add_u64 v[176:177], s[6:7], 0, v[166:167]
	s_add_i32 m0, s75, 0xe000
	s_nop 0
	global_load_lds_dwordx4 v[176:177], off
	s_waitcnt vmcnt(8)
	s_waitcnt lgkmcnt(0)
	s_barrier
	v_mfma_f32_16x16x32_bf16 v[124:127], v[128:131], v[172:175], v[124:127]
	v_mfma_f32_16x16x32_bf16 v[120:123], v[136:139], v[172:175], v[120:123]
	v_mfma_f32_16x16x32_bf16 v[108:111], v[128:131], v[184:187], v[108:111]
	v_mfma_f32_16x16x32_bf16 v[104:107], v[136:139], v[184:187], v[104:107]
	v_mfma_f32_16x16x32_bf16 v[92:95], v[128:131], v[192:195], v[92:95]
	v_mfma_f32_16x16x32_bf16 v[88:91], v[136:139], v[192:195], v[88:91]
	v_mfma_f32_16x16x32_bf16 v[76:79], v[128:131], v[206:209], v[76:79]
	v_mfma_f32_16x16x32_bf16 v[72:75], v[136:139], v[206:209], v[72:75]
	v_mfma_f32_16x16x32_bf16 v[124:127], v[132:135], v[180:183], v[124:127]
	v_mfma_f32_16x16x32_bf16 v[120:123], v[142:145], v[180:183], v[120:123]
	v_mfma_f32_16x16x32_bf16 v[108:111], v[132:135], v[188:191], v[108:111]
	v_mfma_f32_16x16x32_bf16 v[104:107], v[142:145], v[188:191], v[104:107]
	v_mfma_f32_16x16x32_bf16 v[92:95], v[132:135], v[200:203], v[92:95]
	v_mfma_f32_16x16x32_bf16 v[88:91], v[142:145], v[200:203], v[88:91]
	v_mfma_f32_16x16x32_bf16 v[76:79], v[132:135], v[210:213], v[76:79]
	v_mfma_f32_16x16x32_bf16 v[72:75], v[142:145], v[210:213], v[72:75]
	v_mfma_f32_16x16x32_bf16 v[116:119], v[146:149], v[172:175], v[116:119]
	v_mfma_f32_16x16x32_bf16 v[112:115], v[154:157], v[172:175], v[112:115]
	v_mfma_f32_16x16x32_bf16 v[100:103], v[146:149], v[184:187], v[100:103]
	v_mfma_f32_16x16x32_bf16 v[96:99], v[154:157], v[184:187], v[96:99]
	v_mfma_f32_16x16x32_bf16 v[84:87], v[146:149], v[192:195], v[84:87]
	v_mfma_f32_16x16x32_bf16 v[80:83], v[154:157], v[192:195], v[80:83]
	v_mfma_f32_16x16x32_bf16 v[68:71], v[146:149], v[206:209], v[68:71]
	v_mfma_f32_16x16x32_bf16 v[64:67], v[154:157], v[206:209], v[64:67]
	v_mfma_f32_16x16x32_bf16 v[116:119], v[150:153], v[180:183], v[116:119]
	v_mfma_f32_16x16x32_bf16 v[112:115], v[168:171], v[180:183], v[112:115]
	v_mfma_f32_16x16x32_bf16 v[100:103], v[150:153], v[188:191], v[100:103]
	v_mfma_f32_16x16x32_bf16 v[96:99], v[168:171], v[188:191], v[96:99]
	v_mfma_f32_16x16x32_bf16 v[84:87], v[150:153], v[200:203], v[84:87]
	v_mfma_f32_16x16x32_bf16 v[80:83], v[168:171], v[200:203], v[80:83]
	v_mfma_f32_16x16x32_bf16 v[68:71], v[150:153], v[210:213], v[68:71]
	v_mfma_f32_16x16x32_bf16 v[64:67], v[168:171], v[210:213], v[64:67]
	s_barrier
	s_add_i32 s35, s35, s74
	v_lshl_add_u64 v[176:177], s[60:61], 0, v[140:141]
	s_mov_b32 m0, s35
	ds_read_b128 v[172:175], v179 offset:16384
	ds_read_b128 v[180:183], v179 offset:17408
	ds_read_b128 v[184:187], v179 offset:18432
	ds_read_b128 v[188:191], v179 offset:19456
	ds_read_b128 v[192:195], v179 offset:20480
	ds_read_b128 v[200:203], v179 offset:21504
	ds_read_b128 v[206:209], v179 offset:22528
	ds_read_b128 v[210:213], v179 offset:23552
	global_load_lds_dwordx4 v[176:177], off
	s_add_i32 m0, s35, 0x2000
	v_lshl_add_u64 v[196:197], s[60:61], 0, v[158:159]
	s_add_u32 s60, s60, s13
	s_addc_u32 s61, s61, 0
	s_add_i32 s35, s57, s74
	global_load_lds_dwordx4 v[196:197], off
	v_lshl_add_u64 v[198:199], s[60:61], 0, v[140:141]
	s_mov_b32 m0, s35
	v_lshl_add_u64 v[204:205], s[60:61], 0, v[158:159]
	global_load_lds_dwordx4 v[198:199], off
	s_add_i32 m0, s35, 0x2000
	v_lshl_add_u64 v[214:215], s[10:11], 0, v[162:163]
	global_load_lds_dwordx4 v[204:205], off
	s_mov_b32 m0, s75
	s_nop 0
	global_load_lds_dwordx4 v[214:215], off
	v_lshl_add_u64 v[214:215], s[10:11], 0, v[160:161]
	s_mov_b32 m0, s26
	s_nop 0
	global_load_lds_dwordx4 v[214:215], off
	s_waitcnt vmcnt(8)
	s_waitcnt lgkmcnt(0)
	s_barrier
	v_mfma_f32_16x16x32_bf16 v[60:63], v[128:131], v[172:175], v[60:63]
	v_mfma_f32_16x16x32_bf16 v[56:59], v[136:139], v[172:175], v[56:59]
	v_mfma_f32_16x16x32_bf16 v[44:47], v[128:131], v[184:187], v[44:47]
	v_mfma_f32_16x16x32_bf16 v[40:43], v[136:139], v[184:187], v[40:43]
	v_mfma_f32_16x16x32_bf16 v[28:31], v[128:131], v[192:195], v[28:31]
	v_mfma_f32_16x16x32_bf16 v[24:27], v[136:139], v[192:195], v[24:27]
	v_mfma_f32_16x16x32_bf16 v[12:15], v[128:131], v[206:209], v[12:15]
	v_mfma_f32_16x16x32_bf16 v[8:11], v[136:139], v[206:209], v[8:11]
	v_mfma_f32_16x16x32_bf16 v[60:63], v[132:135], v[180:183], v[60:63]
	v_mfma_f32_16x16x32_bf16 v[56:59], v[142:145], v[180:183], v[56:59]
	v_mfma_f32_16x16x32_bf16 v[44:47], v[132:135], v[188:191], v[44:47]
	v_mfma_f32_16x16x32_bf16 v[40:43], v[142:145], v[188:191], v[40:43]
	v_mfma_f32_16x16x32_bf16 v[28:31], v[132:135], v[200:203], v[28:31]
	v_mfma_f32_16x16x32_bf16 v[24:27], v[142:145], v[200:203], v[24:27]
	v_mfma_f32_16x16x32_bf16 v[12:15], v[132:135], v[210:213], v[12:15]
	v_mfma_f32_16x16x32_bf16 v[8:11], v[142:145], v[210:213], v[8:11]
	v_mfma_f32_16x16x32_bf16 v[52:55], v[146:149], v[172:175], v[52:55]
	v_mfma_f32_16x16x32_bf16 v[48:51], v[154:157], v[172:175], v[48:51]
	v_mfma_f32_16x16x32_bf16 v[36:39], v[146:149], v[184:187], v[36:39]
	v_mfma_f32_16x16x32_bf16 v[32:35], v[154:157], v[184:187], v[32:35]
	v_mfma_f32_16x16x32_bf16 v[20:23], v[146:149], v[192:195], v[20:23]
	v_mfma_f32_16x16x32_bf16 v[16:19], v[154:157], v[192:195], v[16:19]
	v_mfma_f32_16x16x32_bf16 v[4:7], v[146:149], v[206:209], v[4:7]
	v_mfma_f32_16x16x32_bf16 v[0:3], v[154:157], v[206:209], v[0:3]
	v_mfma_f32_16x16x32_bf16 v[52:55], v[150:153], v[180:183], v[52:55]
	v_mfma_f32_16x16x32_bf16 v[48:51], v[168:171], v[180:183], v[48:51]
	v_mfma_f32_16x16x32_bf16 v[36:39], v[150:153], v[188:191], v[36:39]
	v_mfma_f32_16x16x32_bf16 v[32:35], v[168:171], v[188:191], v[32:35]
	v_mfma_f32_16x16x32_bf16 v[20:23], v[150:153], v[200:203], v[20:23]
	v_mfma_f32_16x16x32_bf16 v[16:19], v[168:171], v[200:203], v[16:19]
	v_mfma_f32_16x16x32_bf16 v[4:7], v[150:153], v[210:213], v[4:7]
	v_mfma_f32_16x16x32_bf16 v[0:3], v[168:171], v[210:213], v[0:3]
	s_barrier
	s_add_i32 s35, 0, 0x18000
	s_add_i32 s57, 0, 0x1c000
	v_add_u32_e32 v142, s35, v178
	v_add_u32_e32 v168, s57, v178
	ds_read_b128 v[128:131], v142
	ds_read_b128 v[132:135], v142 offset:1024
	ds_read_b128 v[136:139], v142 offset:2048
	ds_read_b128 v[142:145], v142 offset:3072
	ds_read_b128 v[146:149], v168
	ds_read_b128 v[150:153], v168 offset:1024
	ds_read_b128 v[154:157], v168 offset:2048
	ds_read_b128 v[168:171], v168 offset:3072
	s_add_u32 s10, s10, s48
	s_addc_u32 s11, s11, 0
	s_mov_b32 m0, s27
	v_lshl_add_u64 v[214:215], s[10:11], 0, v[162:163]
	ds_read_b128 v[172:175], v179 offset:32768
	ds_read_b128 v[180:183], v179 offset:33792
	ds_read_b128 v[184:187], v179 offset:34816
	ds_read_b128 v[188:191], v179 offset:35840
	ds_read_b128 v[192:195], v179 offset:36864
	ds_read_b128 v[200:203], v179 offset:37888
	ds_read_b128 v[206:209], v179 offset:38912
	ds_read_b128 v[210:213], v179 offset:39936
	global_load_lds_dwordx4 v[214:215], off
	v_lshl_add_u64 v[214:215], s[10:11], 0, v[160:161]
	s_mov_b32 m0, s15
	s_nop 0
	global_load_lds_dwordx4 v[214:215], off
	s_waitcnt vmcnt(8)
	s_waitcnt lgkmcnt(0)
	s_barrier
	v_mfma_f32_16x16x32_bf16 v[124:127], v[128:131], v[172:175], v[124:127]
	v_mfma_f32_16x16x32_bf16 v[120:123], v[136:139], v[172:175], v[120:123]
	v_mfma_f32_16x16x32_bf16 v[108:111], v[128:131], v[184:187], v[108:111]
	v_mfma_f32_16x16x32_bf16 v[104:107], v[136:139], v[184:187], v[104:107]
	v_mfma_f32_16x16x32_bf16 v[92:95], v[128:131], v[192:195], v[92:95]
	v_mfma_f32_16x16x32_bf16 v[88:91], v[136:139], v[192:195], v[88:91]
	v_mfma_f32_16x16x32_bf16 v[76:79], v[128:131], v[206:209], v[76:79]
	v_mfma_f32_16x16x32_bf16 v[72:75], v[136:139], v[206:209], v[72:75]
	v_mfma_f32_16x16x32_bf16 v[124:127], v[132:135], v[180:183], v[124:127]
	v_mfma_f32_16x16x32_bf16 v[120:123], v[142:145], v[180:183], v[120:123]
	v_mfma_f32_16x16x32_bf16 v[108:111], v[132:135], v[188:191], v[108:111]
	v_mfma_f32_16x16x32_bf16 v[104:107], v[142:145], v[188:191], v[104:107]
	v_mfma_f32_16x16x32_bf16 v[92:95], v[132:135], v[200:203], v[92:95]
	v_mfma_f32_16x16x32_bf16 v[88:91], v[142:145], v[200:203], v[88:91]
	v_mfma_f32_16x16x32_bf16 v[76:79], v[132:135], v[210:213], v[76:79]
	v_mfma_f32_16x16x32_bf16 v[72:75], v[142:145], v[210:213], v[72:75]
	v_mfma_f32_16x16x32_bf16 v[116:119], v[146:149], v[172:175], v[116:119]
	v_mfma_f32_16x16x32_bf16 v[112:115], v[154:157], v[172:175], v[112:115]
	v_mfma_f32_16x16x32_bf16 v[100:103], v[146:149], v[184:187], v[100:103]
	v_mfma_f32_16x16x32_bf16 v[96:99], v[154:157], v[184:187], v[96:99]
	v_mfma_f32_16x16x32_bf16 v[84:87], v[146:149], v[192:195], v[84:87]
	v_mfma_f32_16x16x32_bf16 v[80:83], v[154:157], v[192:195], v[80:83]
	v_mfma_f32_16x16x32_bf16 v[68:71], v[146:149], v[206:209], v[68:71]
	v_mfma_f32_16x16x32_bf16 v[64:67], v[154:157], v[206:209], v[64:67]
	v_mfma_f32_16x16x32_bf16 v[116:119], v[150:153], v[180:183], v[116:119]
	v_mfma_f32_16x16x32_bf16 v[112:115], v[168:171], v[180:183], v[112:115]
	v_mfma_f32_16x16x32_bf16 v[100:103], v[150:153], v[188:191], v[100:103]
	v_mfma_f32_16x16x32_bf16 v[96:99], v[168:171], v[188:191], v[96:99]
	v_mfma_f32_16x16x32_bf16 v[84:87], v[150:153], v[200:203], v[84:87]
	v_mfma_f32_16x16x32_bf16 v[80:83], v[168:171], v[200:203], v[80:83]
	v_mfma_f32_16x16x32_bf16 v[68:71], v[150:153], v[210:213], v[68:71]
	v_mfma_f32_16x16x32_bf16 v[64:67], v[168:171], v[210:213], v[64:67]
	s_barrier
	s_add_i32 s10, s35, s74
	v_lshl_add_u64 v[176:177], v[176:177], 0, s[36:37]
	s_mov_b32 m0, s10
	ds_read_b128 v[172:175], v179 offset:49152
	ds_read_b128 v[180:183], v179 offset:50176
	ds_read_b128 v[184:187], v179 offset:51200
	ds_read_b128 v[188:191], v179 offset:52224
	ds_read_b128 v[192:195], v179 offset:53248
	ds_read_b128 v[200:203], v179 offset:54272
	ds_read_b128 v[206:209], v179 offset:55296
	ds_read_b128 v[210:213], v179 offset:56320
	global_load_lds_dwordx4 v[176:177], off
	v_lshl_add_u64 v[176:177], v[196:197], 0, s[36:37]
	s_add_i32 m0, s10, 0x2000
	s_add_i32 s10, s57, s74
	global_load_lds_dwordx4 v[176:177], off
	v_lshl_add_u64 v[176:177], v[198:199], 0, s[36:37]
	s_mov_b32 m0, s10
	s_nop 0
	global_load_lds_dwordx4 v[176:177], off
	v_lshl_add_u64 v[176:177], v[204:205], 0, s[36:37]
	s_add_i32 m0, s10, 0x2000
	s_nop 0
	global_load_lds_dwordx4 v[176:177], off
	v_lshl_add_u64 v[176:177], s[8:9], 0, v[162:163]
	s_mov_b32 m0, s28
	s_nop 0
	global_load_lds_dwordx4 v[176:177], off
	v_lshl_add_u64 v[176:177], s[8:9], 0, v[160:161]
	s_mov_b32 m0, s29
	s_nop 0
	global_load_lds_dwordx4 v[176:177], off
	s_waitcnt vmcnt(8)
	s_waitcnt lgkmcnt(0)
	s_barrier
	v_mfma_f32_16x16x32_bf16 v[60:63], v[128:131], v[172:175], v[60:63]
	v_mfma_f32_16x16x32_bf16 v[56:59], v[136:139], v[172:175], v[56:59]
	v_mfma_f32_16x16x32_bf16 v[44:47], v[128:131], v[184:187], v[44:47]
	v_mfma_f32_16x16x32_bf16 v[40:43], v[136:139], v[184:187], v[40:43]
	v_mfma_f32_16x16x32_bf16 v[28:31], v[128:131], v[192:195], v[28:31]
	v_mfma_f32_16x16x32_bf16 v[24:27], v[136:139], v[192:195], v[24:27]
	v_mfma_f32_16x16x32_bf16 v[12:15], v[128:131], v[206:209], v[12:15]
	v_mfma_f32_16x16x32_bf16 v[8:11], v[136:139], v[206:209], v[8:11]
	v_mfma_f32_16x16x32_bf16 v[60:63], v[132:135], v[180:183], v[60:63]
	v_mfma_f32_16x16x32_bf16 v[56:59], v[142:145], v[180:183], v[56:59]
	v_mfma_f32_16x16x32_bf16 v[44:47], v[132:135], v[188:191], v[44:47]
	v_mfma_f32_16x16x32_bf16 v[40:43], v[142:145], v[188:191], v[40:43]
	v_mfma_f32_16x16x32_bf16 v[28:31], v[132:135], v[200:203], v[28:31]
	v_mfma_f32_16x16x32_bf16 v[24:27], v[142:145], v[200:203], v[24:27]
	v_mfma_f32_16x16x32_bf16 v[12:15], v[132:135], v[210:213], v[12:15]
	v_mfma_f32_16x16x32_bf16 v[8:11], v[142:145], v[210:213], v[8:11]
	v_mfma_f32_16x16x32_bf16 v[52:55], v[146:149], v[172:175], v[52:55]
	v_mfma_f32_16x16x32_bf16 v[48:51], v[154:157], v[172:175], v[48:51]
	v_mfma_f32_16x16x32_bf16 v[36:39], v[146:149], v[184:187], v[36:39]
	v_mfma_f32_16x16x32_bf16 v[32:35], v[154:157], v[184:187], v[32:35]
	v_mfma_f32_16x16x32_bf16 v[20:23], v[146:149], v[192:195], v[20:23]
	v_mfma_f32_16x16x32_bf16 v[16:19], v[154:157], v[192:195], v[16:19]
	v_mfma_f32_16x16x32_bf16 v[4:7], v[146:149], v[206:209], v[4:7]
	v_mfma_f32_16x16x32_bf16 v[0:3], v[154:157], v[206:209], v[0:3]
	v_mfma_f32_16x16x32_bf16 v[52:55], v[150:153], v[180:183], v[52:55]
	v_mfma_f32_16x16x32_bf16 v[48:51], v[168:171], v[180:183], v[48:51]
	v_mfma_f32_16x16x32_bf16 v[36:39], v[150:153], v[188:191], v[36:39]
	v_mfma_f32_16x16x32_bf16 v[32:35], v[168:171], v[188:191], v[32:35]
	v_mfma_f32_16x16x32_bf16 v[20:23], v[150:153], v[200:203], v[20:23]
	v_mfma_f32_16x16x32_bf16 v[16:19], v[168:171], v[200:203], v[16:19]
	v_mfma_f32_16x16x32_bf16 v[4:7], v[150:153], v[210:213], v[4:7]
	v_mfma_f32_16x16x32_bf16 v[0:3], v[168:171], v[210:213], v[0:3]
	s_barrier
	s_add_u32 s24, s24, 0x100
	s_addc_u32 s38, s38, 0
	s_add_u32 s6, s6, 0x10000
	s_addc_u32 s7, s7, 0
	s_cmp_ge_u32 s56, s12
	s_mov_b32 s8, s56
	s_cbranch_scc0 .LBB0_333
	s_nop 0
	s_and_b64 vcc, exec, s[52:53]
	s_cbranch_vccz .LBB0_336
	s_barrier

.LBB0_375:
	s_add_i32 s24, s8, 2
	s_add_u32 s35, s6, 0x80
	s_addc_u32 s9, s7, 0
	s_add_i32 s38, 0, 0x10000
	s_cmp_eq_u32 s94, s8
	s_cselect_b32 s9, s43, s9
	s_cselect_b32 s8, s42, s35
	s_cselect_b32 s57, s55, s11
	s_cselect_b32 s56, s54, s10
	s_add_i32 s35, 0, 0x14000
	v_add_u32_e32 v142, s38, v178
	v_add_u32_e32 v168, s35, v178
	ds_read_b128 v[128:131], v142
	ds_read_b128 v[132:135], v142 offset:1024
	ds_read_b128 v[136:139], v142 offset:2048
	ds_read_b128 v[142:145], v142 offset:3072
	ds_read_b128 v[146:149], v168
	ds_read_b128 v[150:153], v168 offset:1024
	ds_read_b128 v[154:157], v168 offset:2048
	ds_read_b128 v[168:171], v168 offset:3072
	v_lshl_add_u64 v[176:177], s[6:7], 0, v[164:165]
	s_add_i32 m0, s15, 0xc000
	ds_read_b128 v[172:175], v179
	ds_read_b128 v[180:183], v179 offset:1024
	ds_read_b128 v[184:187], v179 offset:2048
	ds_read_b128 v[188:191], v179 offset:3072
	ds_read_b128 v[192:195], v179 offset:4096
	ds_read_b128 v[200:203], v179 offset:5120
	ds_read_b128 v[206:209], v179 offset:6144
	ds_read_b128 v[210:213], v179 offset:7168
	global_load_lds_dwordx4 v[176:177], off
	v_lshl_add_u64 v[176:177], s[6:7], 0, v[166:167]
	s_add_i32 m0, s15, 0xe000
	s_nop 0
	global_load_lds_dwordx4 v[176:177], off
	s_waitcnt vmcnt(8)
	s_waitcnt lgkmcnt(0)
	s_barrier
	v_mfma_f32_16x16x32_bf16 v[124:127], v[128:131], v[172:175], v[124:127]
	v_mfma_f32_16x16x32_bf16 v[120:123], v[136:139], v[172:175], v[120:123]
	v_mfma_f32_16x16x32_bf16 v[108:111], v[128:131], v[184:187], v[108:111]
	v_mfma_f32_16x16x32_bf16 v[104:107], v[136:139], v[184:187], v[104:107]
	v_mfma_f32_16x16x32_bf16 v[92:95], v[128:131], v[192:195], v[92:95]
	v_mfma_f32_16x16x32_bf16 v[88:91], v[136:139], v[192:195], v[88:91]
	v_mfma_f32_16x16x32_bf16 v[76:79], v[128:131], v[206:209], v[76:79]
	v_mfma_f32_16x16x32_bf16 v[72:75], v[136:139], v[206:209], v[72:75]
	v_mfma_f32_16x16x32_bf16 v[124:127], v[132:135], v[180:183], v[124:127]
	v_mfma_f32_16x16x32_bf16 v[120:123], v[142:145], v[180:183], v[120:123]
	v_mfma_f32_16x16x32_bf16 v[108:111], v[132:135], v[188:191], v[108:111]
	v_mfma_f32_16x16x32_bf16 v[104:107], v[142:145], v[188:191], v[104:107]
	v_mfma_f32_16x16x32_bf16 v[92:95], v[132:135], v[200:203], v[92:95]
	v_mfma_f32_16x16x32_bf16 v[88:91], v[142:145], v[200:203], v[88:91]
	v_mfma_f32_16x16x32_bf16 v[76:79], v[132:135], v[210:213], v[76:79]
	v_mfma_f32_16x16x32_bf16 v[72:75], v[142:145], v[210:213], v[72:75]
	v_mfma_f32_16x16x32_bf16 v[116:119], v[146:149], v[172:175], v[116:119]
	v_mfma_f32_16x16x32_bf16 v[112:115], v[154:157], v[172:175], v[112:115]
	v_mfma_f32_16x16x32_bf16 v[100:103], v[146:149], v[184:187], v[100:103]
	v_mfma_f32_16x16x32_bf16 v[96:99], v[154:157], v[184:187], v[96:99]
	v_mfma_f32_16x16x32_bf16 v[84:87], v[146:149], v[192:195], v[84:87]
	v_mfma_f32_16x16x32_bf16 v[80:83], v[154:157], v[192:195], v[80:83]
	v_mfma_f32_16x16x32_bf16 v[68:71], v[146:149], v[206:209], v[68:71]
	v_mfma_f32_16x16x32_bf16 v[64:67], v[154:157], v[206:209], v[64:67]
	v_mfma_f32_16x16x32_bf16 v[116:119], v[150:153], v[180:183], v[116:119]
	v_mfma_f32_16x16x32_bf16 v[112:115], v[168:171], v[180:183], v[112:115]
	v_mfma_f32_16x16x32_bf16 v[100:103], v[150:153], v[188:191], v[100:103]
	v_mfma_f32_16x16x32_bf16 v[96:99], v[168:171], v[188:191], v[96:99]
	v_mfma_f32_16x16x32_bf16 v[84:87], v[150:153], v[200:203], v[84:87]
	v_mfma_f32_16x16x32_bf16 v[80:83], v[168:171], v[200:203], v[80:83]
	v_mfma_f32_16x16x32_bf16 v[68:71], v[150:153], v[210:213], v[68:71]
	v_mfma_f32_16x16x32_bf16 v[64:67], v[168:171], v[210:213], v[64:67]
	s_barrier
	s_add_i32 s38, s38, s75
	v_lshl_add_u64 v[176:177], s[56:57], 0, v[140:141]
	s_mov_b32 m0, s38
	ds_read_b128 v[172:175], v179 offset:16384
	ds_read_b128 v[180:183], v179 offset:17408
	ds_read_b128 v[184:187], v179 offset:18432
	ds_read_b128 v[188:191], v179 offset:19456
	ds_read_b128 v[192:195], v179 offset:20480
	ds_read_b128 v[200:203], v179 offset:21504
	ds_read_b128 v[206:209], v179 offset:22528
	ds_read_b128 v[210:213], v179 offset:23552
	global_load_lds_dwordx4 v[176:177], off
	s_add_i32 m0, s38, 0x2000
	v_lshl_add_u64 v[196:197], s[56:57], 0, v[158:159]
	s_add_u32 s56, s56, s13
	s_addc_u32 s57, s57, 0
	s_add_i32 s35, s35, s75
	global_load_lds_dwordx4 v[196:197], off
	v_lshl_add_u64 v[198:199], s[56:57], 0, v[140:141]
	s_mov_b32 m0, s35
	v_lshl_add_u64 v[204:205], s[56:57], 0, v[158:159]
	global_load_lds_dwordx4 v[198:199], off
	s_add_i32 m0, s35, 0x2000
	v_lshl_add_u64 v[214:215], s[8:9], 0, v[162:163]
	global_load_lds_dwordx4 v[204:205], off
	s_mov_b32 m0, s15
	v_lshl_add_u64 v[216:217], s[8:9], 0, v[160:161]
	global_load_lds_dwordx4 v[214:215], off
	s_mov_b32 m0, s26
	s_nop 0
	global_load_lds_dwordx4 v[216:217], off
	s_waitcnt vmcnt(8)
	s_waitcnt lgkmcnt(0)
	s_barrier
	v_mfma_f32_16x16x32_bf16 v[60:63], v[128:131], v[172:175], v[60:63]
	v_mfma_f32_16x16x32_bf16 v[56:59], v[136:139], v[172:175], v[56:59]
	v_mfma_f32_16x16x32_bf16 v[44:47], v[128:131], v[184:187], v[44:47]
	v_mfma_f32_16x16x32_bf16 v[40:43], v[136:139], v[184:187], v[40:43]
	v_mfma_f32_16x16x32_bf16 v[28:31], v[128:131], v[192:195], v[28:31]
	v_mfma_f32_16x16x32_bf16 v[24:27], v[136:139], v[192:195], v[24:27]
	v_mfma_f32_16x16x32_bf16 v[12:15], v[128:131], v[206:209], v[12:15]
	v_mfma_f32_16x16x32_bf16 v[8:11], v[136:139], v[206:209], v[8:11]
	v_mfma_f32_16x16x32_bf16 v[60:63], v[132:135], v[180:183], v[60:63]
	v_mfma_f32_16x16x32_bf16 v[56:59], v[142:145], v[180:183], v[56:59]
	v_mfma_f32_16x16x32_bf16 v[44:47], v[132:135], v[188:191], v[44:47]
	v_mfma_f32_16x16x32_bf16 v[40:43], v[142:145], v[188:191], v[40:43]
	v_mfma_f32_16x16x32_bf16 v[28:31], v[132:135], v[200:203], v[28:31]
	v_mfma_f32_16x16x32_bf16 v[24:27], v[142:145], v[200:203], v[24:27]
	v_mfma_f32_16x16x32_bf16 v[12:15], v[132:135], v[210:213], v[12:15]
	v_mfma_f32_16x16x32_bf16 v[8:11], v[142:145], v[210:213], v[8:11]
	v_mfma_f32_16x16x32_bf16 v[52:55], v[146:149], v[172:175], v[52:55]
	v_mfma_f32_16x16x32_bf16 v[48:51], v[154:157], v[172:175], v[48:51]
	v_mfma_f32_16x16x32_bf16 v[36:39], v[146:149], v[184:187], v[36:39]
	v_mfma_f32_16x16x32_bf16 v[32:35], v[154:157], v[184:187], v[32:35]
	v_mfma_f32_16x16x32_bf16 v[20:23], v[146:149], v[192:195], v[20:23]
	v_mfma_f32_16x16x32_bf16 v[16:19], v[154:157], v[192:195], v[16:19]
	v_mfma_f32_16x16x32_bf16 v[4:7], v[146:149], v[206:209], v[4:7]
	v_mfma_f32_16x16x32_bf16 v[0:3], v[154:157], v[206:209], v[0:3]
	v_mfma_f32_16x16x32_bf16 v[52:55], v[150:153], v[180:183], v[52:55]
	v_mfma_f32_16x16x32_bf16 v[48:51], v[168:171], v[180:183], v[48:51]
	v_mfma_f32_16x16x32_bf16 v[36:39], v[150:153], v[188:191], v[36:39]
	v_mfma_f32_16x16x32_bf16 v[32:35], v[168:171], v[188:191], v[32:35]
	v_mfma_f32_16x16x32_bf16 v[20:23], v[150:153], v[200:203], v[20:23]
	v_mfma_f32_16x16x32_bf16 v[16:19], v[168:171], v[200:203], v[16:19]
	v_mfma_f32_16x16x32_bf16 v[4:7], v[150:153], v[210:213], v[4:7]
	v_mfma_f32_16x16x32_bf16 v[0:3], v[168:171], v[210:213], v[0:3]
	s_barrier
	s_add_i32 s35, 0, 0x18000
	s_add_i32 s38, 0, 0x1c000
	v_add_u32_e32 v142, s35, v178
	v_add_u32_e32 v168, s38, v178
	ds_read_b128 v[128:131], v142
	ds_read_b128 v[132:135], v142 offset:1024
	ds_read_b128 v[136:139], v142 offset:2048
	ds_read_b128 v[142:145], v142 offset:3072
	ds_read_b128 v[146:149], v168
	ds_read_b128 v[150:153], v168 offset:1024
	ds_read_b128 v[154:157], v168 offset:2048
	ds_read_b128 v[168:171], v168 offset:3072
	s_add_u32 s8, s8, s48
	s_addc_u32 s9, s9, 0
	s_mov_b32 m0, s27
	v_lshl_add_u64 v[218:219], s[8:9], 0, v[162:163]
	ds_read_b128 v[172:175], v179 offset:32768
	ds_read_b128 v[180:183], v179 offset:33792
	ds_read_b128 v[184:187], v179 offset:34816
	ds_read_b128 v[188:191], v179 offset:35840
	ds_read_b128 v[192:195], v179 offset:36864
	ds_read_b128 v[200:203], v179 offset:37888
	ds_read_b128 v[206:209], v179 offset:38912
	ds_read_b128 v[210:213], v179 offset:39936
	global_load_lds_dwordx4 v[218:219], off
	v_lshl_add_u64 v[218:219], s[8:9], 0, v[160:161]
	s_mov_b32 m0, s28
	s_nop 0
	global_load_lds_dwordx4 v[218:219], off
	s_waitcnt vmcnt(8)
	s_waitcnt lgkmcnt(0)
	s_barrier
	v_mfma_f32_16x16x32_bf16 v[124:127], v[128:131], v[172:175], v[124:127]
	v_mfma_f32_16x16x32_bf16 v[120:123], v[136:139], v[172:175], v[120:123]
	v_mfma_f32_16x16x32_bf16 v[108:111], v[128:131], v[184:187], v[108:111]
	v_mfma_f32_16x16x32_bf16 v[104:107], v[136:139], v[184:187], v[104:107]
	v_mfma_f32_16x16x32_bf16 v[92:95], v[128:131], v[192:195], v[92:95]
	v_mfma_f32_16x16x32_bf16 v[88:91], v[136:139], v[192:195], v[88:91]
	v_mfma_f32_16x16x32_bf16 v[76:79], v[128:131], v[206:209], v[76:79]
	v_mfma_f32_16x16x32_bf16 v[72:75], v[136:139], v[206:209], v[72:75]
	v_mfma_f32_16x16x32_bf16 v[124:127], v[132:135], v[180:183], v[124:127]
	v_mfma_f32_16x16x32_bf16 v[120:123], v[142:145], v[180:183], v[120:123]
	v_mfma_f32_16x16x32_bf16 v[108:111], v[132:135], v[188:191], v[108:111]
	v_mfma_f32_16x16x32_bf16 v[104:107], v[142:145], v[188:191], v[104:107]
	v_mfma_f32_16x16x32_bf16 v[92:95], v[132:135], v[200:203], v[92:95]
	v_mfma_f32_16x16x32_bf16 v[88:91], v[142:145], v[200:203], v[88:91]
	v_mfma_f32_16x16x32_bf16 v[76:79], v[132:135], v[210:213], v[76:79]
	v_mfma_f32_16x16x32_bf16 v[72:75], v[142:145], v[210:213], v[72:75]
	v_mfma_f32_16x16x32_bf16 v[116:119], v[146:149], v[172:175], v[116:119]
	v_mfma_f32_16x16x32_bf16 v[112:115], v[154:157], v[172:175], v[112:115]
	v_mfma_f32_16x16x32_bf16 v[100:103], v[146:149], v[184:187], v[100:103]
	v_mfma_f32_16x16x32_bf16 v[96:99], v[154:157], v[184:187], v[96:99]
	v_mfma_f32_16x16x32_bf16 v[84:87], v[146:149], v[192:195], v[84:87]
	v_mfma_f32_16x16x32_bf16 v[80:83], v[154:157], v[192:195], v[80:83]
	v_mfma_f32_16x16x32_bf16 v[68:71], v[146:149], v[206:209], v[68:71]
	v_mfma_f32_16x16x32_bf16 v[64:67], v[154:157], v[206:209], v[64:67]
	v_mfma_f32_16x16x32_bf16 v[116:119], v[150:153], v[180:183], v[116:119]
	v_mfma_f32_16x16x32_bf16 v[112:115], v[168:171], v[180:183], v[112:115]
	v_mfma_f32_16x16x32_bf16 v[100:103], v[150:153], v[188:191], v[100:103]
	v_mfma_f32_16x16x32_bf16 v[96:99], v[168:171], v[188:191], v[96:99]
	v_mfma_f32_16x16x32_bf16 v[84:87], v[150:153], v[200:203], v[84:87]
	v_mfma_f32_16x16x32_bf16 v[80:83], v[168:171], v[200:203], v[80:83]
	v_mfma_f32_16x16x32_bf16 v[68:71], v[150:153], v[210:213], v[68:71]
	v_mfma_f32_16x16x32_bf16 v[64:67], v[168:171], v[210:213], v[64:67]
	s_barrier
	s_add_i32 s8, s35, s75
	v_lshl_add_u64 v[176:177], v[176:177], 0, s[36:37]
	s_mov_b32 m0, s8
	ds_read_b128 v[172:175], v179 offset:49152
	ds_read_b128 v[180:183], v179 offset:50176
	ds_read_b128 v[184:187], v179 offset:51200
	ds_read_b128 v[188:191], v179 offset:52224
	ds_read_b128 v[192:195], v179 offset:53248
	ds_read_b128 v[200:203], v179 offset:54272
	ds_read_b128 v[206:209], v179 offset:55296
	ds_read_b128 v[210:213], v179 offset:56320
	global_load_lds_dwordx4 v[176:177], off
	v_lshl_add_u64 v[176:177], v[196:197], 0, s[36:37]
	s_add_i32 m0, s8, 0x2000
	s_add_i32 s8, s38, s75
	global_load_lds_dwordx4 v[176:177], off
	v_lshl_add_u64 v[176:177], v[198:199], 0, s[36:37]
	s_mov_b32 m0, s8
	s_nop 0
	global_load_lds_dwordx4 v[176:177], off
	v_lshl_add_u64 v[176:177], v[204:205], 0, s[36:37]
	s_add_i32 m0, s8, 0x2000
	s_nop 0
	global_load_lds_dwordx4 v[176:177], off
	v_lshl_add_u64 v[176:177], v[214:215], 0, s[36:37]
	s_mov_b32 m0, s29
	s_nop 0
	global_load_lds_dwordx4 v[176:177], off
	v_lshl_add_u64 v[176:177], v[216:217], 0, s[36:37]
	s_mov_b32 m0, s58
	s_nop 0
	global_load_lds_dwordx4 v[176:177], off
	s_waitcnt vmcnt(8)
	s_waitcnt lgkmcnt(0)
	s_barrier
	v_mfma_f32_16x16x32_bf16 v[60:63], v[128:131], v[172:175], v[60:63]
	v_mfma_f32_16x16x32_bf16 v[56:59], v[136:139], v[172:175], v[56:59]
	v_mfma_f32_16x16x32_bf16 v[44:47], v[128:131], v[184:187], v[44:47]
	v_mfma_f32_16x16x32_bf16 v[40:43], v[136:139], v[184:187], v[40:43]
	v_mfma_f32_16x16x32_bf16 v[28:31], v[128:131], v[192:195], v[28:31]
	v_mfma_f32_16x16x32_bf16 v[24:27], v[136:139], v[192:195], v[24:27]
	v_mfma_f32_16x16x32_bf16 v[12:15], v[128:131], v[206:209], v[12:15]
	v_mfma_f32_16x16x32_bf16 v[8:11], v[136:139], v[206:209], v[8:11]
	v_mfma_f32_16x16x32_bf16 v[60:63], v[132:135], v[180:183], v[60:63]
	v_mfma_f32_16x16x32_bf16 v[56:59], v[142:145], v[180:183], v[56:59]
	v_mfma_f32_16x16x32_bf16 v[44:47], v[132:135], v[188:191], v[44:47]
	v_mfma_f32_16x16x32_bf16 v[40:43], v[142:145], v[188:191], v[40:43]
	v_mfma_f32_16x16x32_bf16 v[28:31], v[132:135], v[200:203], v[28:31]
	v_mfma_f32_16x16x32_bf16 v[24:27], v[142:145], v[200:203], v[24:27]
	v_mfma_f32_16x16x32_bf16 v[12:15], v[132:135], v[210:213], v[12:15]
	v_mfma_f32_16x16x32_bf16 v[8:11], v[142:145], v[210:213], v[8:11]
	v_mfma_f32_16x16x32_bf16 v[52:55], v[146:149], v[172:175], v[52:55]
	v_mfma_f32_16x16x32_bf16 v[48:51], v[154:157], v[172:175], v[48:51]
	v_mfma_f32_16x16x32_bf16 v[36:39], v[146:149], v[184:187], v[36:39]
	v_mfma_f32_16x16x32_bf16 v[32:35], v[154:157], v[184:187], v[32:35]
	v_mfma_f32_16x16x32_bf16 v[20:23], v[146:149], v[192:195], v[20:23]
	v_mfma_f32_16x16x32_bf16 v[16:19], v[154:157], v[192:195], v[16:19]
	v_mfma_f32_16x16x32_bf16 v[4:7], v[146:149], v[206:209], v[4:7]
	v_mfma_f32_16x16x32_bf16 v[0:3], v[154:157], v[206:209], v[0:3]
	v_mfma_f32_16x16x32_bf16 v[52:55], v[150:153], v[180:183], v[52:55]
	v_mfma_f32_16x16x32_bf16 v[48:51], v[168:171], v[180:183], v[48:51]
	v_mfma_f32_16x16x32_bf16 v[36:39], v[150:153], v[188:191], v[36:39]
	v_mfma_f32_16x16x32_bf16 v[32:35], v[168:171], v[188:191], v[32:35]
	v_mfma_f32_16x16x32_bf16 v[20:23], v[150:153], v[200:203], v[20:23]
	v_mfma_f32_16x16x32_bf16 v[16:19], v[168:171], v[200:203], v[16:19]
	v_mfma_f32_16x16x32_bf16 v[4:7], v[150:153], v[210:213], v[4:7]
	v_mfma_f32_16x16x32_bf16 v[0:3], v[168:171], v[210:213], v[0:3]
	s_barrier
	s_add_u32 s6, s6, 0x100
	s_addc_u32 s7, s7, 0
	s_add_u32 s10, s10, 0x100
	s_addc_u32 s11, s11, 0
	s_cmp_ge_u32 s24, s12
	s_mov_b32 s8, s24
	s_cbranch_scc0 .LBB0_375
	s_nop 0
	s_and_b64 vcc, exec, s[52:53]
	s_cbranch_vccz .LBB0_378
	s_barrier
